# GU unit header: division by the (always 4) row-group height replaced by shift/mask
# baseline (speedup 1.0000x reference)
;     __host__ __device__ bool next(int i, Unit& u) const {
;         const long L = (long)i * G + c; if (L >= nwg) return false;
;         int wgid = (int)L; { const int q = nwg / NXCD, r = nwg % NXCD, xcd = wgid % NXCD, off = wgid / NXCD; wgid = (xcd < r ? xcd * (q + 1) : r * (q + 1) + (xcd - r) * q) + off; }
;         const int nig = WGM * nN, gid = wgid / nig, fm = gid * WGM, gsz = (nM - fm) < WGM ? (nM - fm) : WGM;
;         u.pm = fm + ((wgid % nig) % gsz); u.pn = (wgid % nig) / gsz; return true;
;     }
.LBB0_1644:
	s_add_i32 s58, 0, 0x10000
	v_add_u32_e32 v162, s58, v165
	s_add_i32 s60, 0, 0x14000
	ds_read_b128 v[132:135], v162
	ds_read_b128 v[136:139], v162 offset:1024
	ds_read_b128 v[140:143], v162 offset:2048
	ds_read_b128 v[180:183], v162 offset:3072
	v_add_u32_e32 v162, s60, v165
	ds_read_b128 v[200:203], v162
	ds_read_b128 v[204:207], v162 offset:1024
	ds_read_b128 v[208:211], v162 offset:2048
	ds_read_b128 v[212:215], v162 offset:3072
	ds_read_b128 v[216:219], v197
	ds_read_b128 v[220:223], v197 offset:1024
	ds_read_b128 v[224:227], v197 offset:2048
	ds_read_b128 v[228:231], v197 offset:3072
	ds_read_b128 v[232:235], v197 offset:4096
	ds_read_b128 v[236:239], v197 offset:5120
	ds_read_b128 v[240:243], v197 offset:6144
	ds_read_b128 v[244:247], v197 offset:7168
	s_add_i32 s35, s35, 1
	s_mul_i32 s6, s35, s23
	s_mul_hi_u32 s7, s35, s22
	s_add_i32 s7, s7, s6
	s_mul_i32 s6, s35, s22
	s_add_u32 s6, s6, s89
	s_addc_u32 s7, s7, s13
	v_mov_b64_e32 v[0:1], 0x580
	v_cmp_lt_i64_e64 s[36:37], s[6:7], v[0:1]
	v_mov_b64_e32 v[0:1], 0x57f
	v_cmp_gt_i64_e32 vcc, s[6:7], v[0:1]
	s_cbranch_vccnz .LBB0_1646
	s_ashr_i32 s7, s6, 31
	s_lshr_b32 s7, s7, 29
	s_add_i32 s7, s6, s7
	s_ashr_i32 s39, s7, 3
	s_and_b32 s7, s7, -8
	s_sub_i32 s6, s6, s7
	s_cmp_lt_i32 s6, 0
	s_movk_i32 s7, 0xb1
	s_cselect_b32 s7, s7, 0xb0
	s_mul_i32 s6, s6, s7
	s_add_i32 s6, s6, s39
	s_mul_hi_i32 s7, s6, 0x2e8ba2e9
	s_lshr_b32 s39, s7, 31
	s_ashr_i32 s7, s7, 4
	s_add_i32 s7, s7, s39
	s_lshl_b32 s39, s7, 2
	s_mulk_i32 s7, 0x58
	s_sub_i32 s6, s6, s7
	s_lshr_b32 s44, s6, 2
	s_and_b32 s6, s6, 3
	s_add_i32 s46, s39, s6
